# attention item start: drop the vmcnt(0) that only waited for the previous item's output-store acks (next item's Q/K DMA now issues under them)
# baseline (speedup 1.0000x reference)
; #define LAS __attribute__((address_space(3)))
; #define SB_WAIT_V(n) asm volatile("s_waitcnt vmcnt(" #n ")" ::: "memory")
; #define SB_WAIT_L0() asm volatile("s_waitcnt lgkmcnt(0)" ::: "memory")
; __device__ __forceinline__ void sb_attn_item(bf16_t* PB, const bf16_t* VT, int b, int h, int qb, int lane, LAS unsigned char* wl  ) {
;     const int j = lane & 31, hi = lane >> 5;
;     const int t = qb * 32 + j;
;     const size_t rowq = (size_t)(b * SEQ + t);
;     LAS unsigned char* kbuf = wl; LAS unsigned char* vbuf = wl + 8192;
;     const bf16_t* kbase_b = PB + (size_t)(b * SEQ) * PBW + C_K + h * 128;
;     const bf16_t* vbase_bh = VT + (size_t)(h * 128) * MTOK + b * SEQ;
;     SB_WAIT_V(0); SB_WAIT_L0();
;     const int koff = j * 256, kx = j & 15;
;     sb_dma_k(PB + (size_t)(b * SEQ) * PBW + C_Q + h * 128, qb * 32, vbuf, lane);
;     sb_dma_k(kbase_b, qb * 32, kbuf, lane);
;     SB_WAIT_V(8);
;     bf16x8 qf[8];
; #pragma unroll
;     for (int kk = 0; kk < 8; ++kk) qf[kk] = *(const LAS bf16x8*)(vbuf + koff + (((2 * kk + hi) ^ kx) << 4));
;     SB_WAIT_L0();
;     sb_dma_v(vbase_bh, qb * 32, vbuf, lane);
;     f32x16 o[4];
; #pragma unroll
;     for (int blk = 0; blk < 4; ++blk)
; #pragma unroll
;         for (int r = 0; r < 16; ++r) o[blk][r] = 0.f;
;     float R = 0.f;
;     const float SCALE2 = 0.08838834764831845f * LOG2E;
;     ...
;         SB_WAIT_V(8);
;         f32x16 s;
; #pragma unroll
;         for (int r = 0; r < 16; ++r) s[r] = 0.f;
;         {
;             bf16x8 kf[8];
; #pragma unroll
;             for (int kk = 0; kk < 8; ++kk) kf[kk] = *(const LAS bf16x8*)(kbuf + koff + (((2 * kk + hi) ^ kx) << 4));
; #pragma unroll
;             for (int kk = 0; kk < 8; ++kk) s = __builtin_amdgcn_mfma_f32_32x32x16_bf16(kf[kk], qf[kk], s, 0, 0, 0);
.LBB0_349:
	s_lshl_b32 s40, s50, 1
	s_and_b32 s40, s40, 0xfffff000
	s_and_b32 s71, s50, 0x7f
	s_and_b32 s33, s50, 0x780
	s_ashr_i32 s41, s40, 31
	s_mul_i32 s43, s40, 0x9000
	s_mul_hi_i32 s42, s40, 0x9000
	s_add_u32 s43, s92, s43
	s_addc_u32 s42, s93, s42
	s_lshl_b32 s69, s33, 1
	s_add_u32 s43, s43, s69
	s_addc_u32 s42, s42, 0
	s_add_u32 s83, s43, 0x2000
	s_addc_u32 s67, s42, 0
	s_lshl_b32 s33, s33, 15
	s_add_u32 s44, s51, s33
	s_addc_u32 s45, s52, 0
	s_nop 0
	v_mov_b32_e32 v0, v150
	s_mul_i32 s33, s71, 0x120000
	s_waitcnt lgkmcnt(0)
	s_add_u32 s43, s43, s33
	v_ashrrev_i32_e32 v1, 4, v0
	s_addc_u32 s46, s42, 0
	v_xor_b32_e32 v2, v1, v0
	v_add_u32_e32 v4, 4, v1
	s_add_u32 s42, s43, 0x1000
	v_mul_lo_u32 v3, v1, s64
	v_lshlrev_b32_e32 v2, 3, v2
	v_xor_b32_e32 v4, v4, v0
	s_addc_u32 s43, s46, 0
	v_and_or_b32 v2, v2, s84, v3
	s_add_i32 s53, s86, 0x2000
	v_add_u32_e32 v5, 0x12000, v3
	v_lshlrev_b32_e32 v4, 3, v4
	v_lshlrev_b32_e32 v2, 1, v2
	s_mov_b32 m0, s53
	v_and_or_b32 v4, v4, s84, v5
	global_load_lds_dwordx4 v2, s[42:43]
	v_lshlrev_b32_e32 v4, 1, v4
	s_mov_b32 m0, s57
	s_add_i32 s81, s86, 0x3000
	global_load_lds_dwordx4 v4, s[42:43]
	v_add_u32_e32 v4, 8, v1
	v_xor_b32_e32 v4, v4, v0
	v_lshlrev_b32_e32 v4, 3, v4
	v_and_or_b32 v4, v4, s84, v5
	v_lshl_add_u32 v4, v4, 1, v254
	s_mov_b32 m0, s58
	v_add_u32_e32 v5, 0x36000, v3
	global_load_lds_dwordx4 v4, s[42:43]
	v_add_u32_e32 v4, 12, v1
	v_xor_b32_e32 v4, v4, v0
	v_lshlrev_b32_e32 v4, 3, v4
	v_and_or_b32 v4, v4, s84, v5
	v_lshlrev_b32_e32 v4, 1, v4
	s_mov_b32 m0, s59
	v_add_u32_e32 v2, 0x90000, v2
	global_load_lds_dwordx4 v4, s[42:43]
	s_mov_b32 m0, s81
	v_add_u32_e32 v3, 0x6c000, v3
	global_load_lds_dwordx4 v2, s[42:43]
	v_add_u32_e32 v2, 20, v1
	v_xor_b32_e32 v2, v2, v0
	v_lshlrev_b32_e32 v2, 3, v2
	v_and_or_b32 v2, v2, s84, v5
	v_lshl_add_u32 v2, v2, 1, v243
	s_mov_b32 m0, s60
	s_add_u32 s48, s83, s33
	global_load_lds_dwordx4 v2, s[42:43]
	v_add_u32_e32 v2, 24, v1
	v_xor_b32_e32 v2, v2, v0
	v_add_u32_e32 v1, 28, v1
	v_lshlrev_b32_e32 v2, 3, v2
	v_xor_b32_e32 v0, v1, v0
	v_and_or_b32 v2, v2, s84, v3
	v_lshlrev_b32_e32 v0, 3, v0
	v_lshlrev_b32_e32 v2, 1, v2
	s_mov_b32 m0, s61
	v_and_or_b32 v0, v0, s84, v3
	global_load_lds_dwordx4 v2, s[42:43]
	v_lshl_add_u32 v0, v0, 1, v254
	s_mov_b32 m0, s62
	s_addc_u32 s49, s67, 0
	global_load_lds_dwordx4 v0, s[42:43]
	v_mov_b32_e32 v0, v150
	s_mov_b32 m0, s86
	v_ashrrev_i32_e32 v1, 4, v0
	v_xor_b32_e32 v2, v1, v0
	v_add_u32_e32 v4, 4, v1
	v_mul_lo_u32 v3, v1, s64
	v_lshlrev_b32_e32 v2, 3, v2
	v_xor_b32_e32 v4, v4, v0
	v_and_or_b32 v2, v2, s84, v3
	v_add_u32_e32 v5, 0x12000, v3
	v_lshlrev_b32_e32 v4, 3, v4
	v_lshlrev_b32_e32 v2, 1, v2
	v_and_or_b32 v4, v4, s84, v5
	s_add_i32 s80, s86, 0x400
	global_load_lds_dwordx4 v2, s[48:49]
	v_lshlrev_b32_e32 v4, 1, v4
	s_mov_b32 m0, s80
	s_add_i32 s33, s86, 0x1000
	global_load_lds_dwordx4 v4, s[48:49]
	v_add_u32_e32 v4, 8, v1
	v_xor_b32_e32 v4, v4, v0
	v_lshlrev_b32_e32 v4, 3, v4
	v_and_or_b32 v4, v4, s84, v5
	v_lshl_add_u32 v4, v4, 1, v254
	s_mov_b32 m0, s63
	v_add_u32_e32 v5, 0x36000, v3
	global_load_lds_dwordx4 v4, s[48:49]
	v_add_u32_e32 v4, 12, v1
	v_xor_b32_e32 v4, v4, v0
	v_lshlrev_b32_e32 v4, 3, v4
	v_and_or_b32 v4, v4, s84, v5
	v_lshlrev_b32_e32 v4, 1, v4
	s_mov_b32 m0, s91
	v_add_u32_e32 v2, 0x90000, v2
	global_load_lds_dwordx4 v4, s[48:49]
	s_mov_b32 m0, s33
	v_add_u32_e32 v3, 0x6c000, v3
	global_load_lds_dwordx4 v2, s[48:49]
	v_add_u32_e32 v2, 20, v1
	v_xor_b32_e32 v2, v2, v0
	v_lshlrev_b32_e32 v2, 3, v2
	v_and_or_b32 v2, v2, s84, v5
	v_lshl_add_u32 v2, v2, 1, v243
	s_mov_b32 m0, s97
	s_lshl_b64 s[42:43], s[40:41], 1
	global_load_lds_dwordx4 v2, s[48:49]
	v_add_u32_e32 v2, 24, v1
	v_xor_b32_e32 v2, v2, v0
	v_add_u32_e32 v1, 28, v1
	v_lshlrev_b32_e32 v2, 3, v2
	v_xor_b32_e32 v0, v1, v0
	v_and_or_b32 v2, v2, s84, v3
	v_lshlrev_b32_e32 v0, 3, v0
	v_lshlrev_b32_e32 v2, 1, v2
	s_mov_b32 m0, s89
	v_and_or_b32 v0, v0, s84, v3
	global_load_lds_dwordx4 v2, s[48:49]
	v_lshl_add_u32 v0, v0, 1, v254
	s_mov_b32 m0, s73
	s_add_u32 s41, s44, s42
	global_load_lds_dwordx4 v0, s[48:49]
	s_waitcnt vmcnt(8)
	v_mov_b32_e32 v0, v150
	ds_read_b128 v[80:83], v169 offset:8192
	ds_read_b128 v[84:87], v170 offset:8192
	ds_read_b128 v[88:91], v171 offset:8192
	ds_read_b128 v[92:95], v172 offset:8192
	ds_read_b128 v[96:99], v173 offset:8192
	ds_read_b128 v[100:103], v174 offset:8192
	ds_read_b128 v[104:107], v175 offset:8192
	ds_read_b128 v[108:111], v176 offset:8192
	s_addc_u32 s43, s45, s43
	s_waitcnt lgkmcnt(0)
	s_lshl_b32 s42, s71, 6
	v_lshlrev_b32_e32 v1, 13, v0
	v_lshlrev_b32_e32 v2, 4, v0
	s_add_u32 s42, s41, s42
	v_and_b32_e32 v1, 0xffff8000, v1
	v_xor_b32_e32 v0, v2, v0
	s_addc_u32 s43, s43, 0
	v_and_or_b32 v0, v0, 48, v1
	s_mov_b32 m0, s53
	v_add_u32_e32 v1, 0x80000, v0
	global_load_lds_dwordx4 v0, s[42:43]
	s_mov_b32 m0, s57
	s_cmp_eq_u32 s71, 0
	global_load_lds_dwordx4 v1, s[42:43]
	v_add_u32_e32 v1, 0x100000, v0
	s_mov_b32 m0, s58
	s_cselect_b64 s[44:45], -1, 0
	global_load_lds_dwordx4 v1, s[42:43]
	v_add_u32_e32 v1, 0x180000, v0
	s_mov_b32 m0, s59
	s_cmp_lg_u32 s71, 0
	global_load_lds_dwordx4 v1, s[42:43]
	v_add_u32_e32 v1, 0x200000, v0
	s_mov_b32 m0, s81
	s_cselect_b64 s[46:47], -1, 0
	global_load_lds_dwordx4 v1, s[42:43]
	v_add_u32_e32 v1, 0x280000, v0
	s_mov_b32 m0, s60
	s_and_b64 vcc, exec, s[44:45]
	global_load_lds_dwordx4 v1, s[42:43]
	v_add_u32_e32 v1, 0x300000, v0
	s_mov_b32 m0, s61
	v_add_u32_e32 v0, 0x380000, v0
	global_load_lds_dwordx4 v1, s[42:43]
	s_mov_b32 m0, s62
	s_nop 0
	global_load_lds_dwordx4 v0, s[42:43]
	s_waitcnt vmcnt(8)
	ds_read_b128 v[0:3], v169
	ds_read_b128 v[16:19], v170
	s_waitcnt lgkmcnt(0)
	v_mfma_f32_32x32x16_bf16 v[0:15], v[0:3], v[80:83], 0
	v_mfma_f32_32x32x16_bf16 v[0:15], v[16:19], v[84:87], v[0:15]
	ds_read_b128 v[16:19], v171
	s_waitcnt lgkmcnt(0)
	v_mfma_f32_32x32x16_bf16 v[0:15], v[16:19], v[88:91], v[0:15]
	ds_read_b128 v[16:19], v172
	s_waitcnt lgkmcnt(0)
	v_mfma_f32_32x32x16_bf16 v[0:15], v[16:19], v[92:95], v[0:15]
	ds_read_b128 v[16:19], v173
	s_waitcnt lgkmcnt(0)
	v_mfma_f32_32x32x16_bf16 v[0:15], v[16:19], v[96:99], v[0:15]
	ds_read_b128 v[16:19], v174
	s_waitcnt lgkmcnt(0)
	v_mfma_f32_32x32x16_bf16 v[0:15], v[16:19], v[100:103], v[0:15]
	ds_read_b128 v[16:19], v175
	s_waitcnt lgkmcnt(0)
	v_mfma_f32_32x32x16_bf16 v[0:15], v[16:19], v[104:107], v[0:15]
	ds_read_b128 v[16:19], v176
	s_waitcnt lgkmcnt(0)
	s_waitcnt lgkmcnt(0)
	v_mfma_f32_32x32x16_bf16 v[0:15], v[16:19], v[108:111], v[0:15]
	s_cbranch_vccnz .LBB0_351
; #define LAS __attribute__((address_space(3)))
; __device__ __forceinline__ void sb_dma_k(const bf16_t* kbase_b  , int s0, LAS unsigned char* kbuf, int lane) {
;     asm volatile("" : "+v"(lane));
;     const char* gb = (const char*)(kbase_b + (size_t)s0 * PBW);
; #pragma unroll
;     for (int c = 0; c < 8; ++c) { const int r = 4 * c + (lane >> 4), chunk = (lane & 15) ^ (r & 15); const unsigned off = (unsigned)(r * PBW + chunk * 8) * 2u;
;         __builtin_amdgcn_global_load_lds((const unsigned*)(gb + off), (LAS unsigned*)(kbuf + c * 1024), 16, 0, 0); }
; }
; __device__ __forceinline__ void sb_attn_item(bf16_t* PB, const bf16_t* VT, int b, int h, int qb, int lane, LAS unsigned char* wl  ) {
;     ...
;         if (kt > 0) sb_dma_k(kbase_b, (kt - 1) * 32, kbuf, lane);
	v_mov_b32_e32 v16, v150
	s_add_u32 s48, s48, 0xffee0000
	v_ashrrev_i32_e32 v17, 4, v16
	v_xor_b32_e32 v18, v17, v16
	v_add_u32_e32 v20, 4, v17
	v_mul_lo_u32 v19, v17, s64
	v_lshlrev_b32_e32 v18, 3, v18
	v_xor_b32_e32 v20, v20, v16
	v_and_or_b32 v18, v18, s84, v19
	v_add_u32_e32 v21, 0x12000, v19
	v_lshlrev_b32_e32 v20, 3, v20
	s_mov_b32 m0, s86
	s_addc_u32 s49, s49, -1
	v_lshlrev_b32_e32 v18, 1, v18
	v_and_or_b32 v20, v20, s84, v21
	global_load_lds_dwordx4 v18, s[48:49]
	v_lshlrev_b32_e32 v20, 1, v20
	s_mov_b32 m0, s80
	v_add_u32_e32 v18, 0x90000, v18
	global_load_lds_dwordx4 v20, s[48:49]
	v_add_u32_e32 v20, 8, v17
	v_xor_b32_e32 v20, v20, v16
	v_lshlrev_b32_e32 v20, 3, v20
	v_and_or_b32 v20, v20, s84, v21
	v_lshl_add_u32 v20, v20, 1, v254
	s_mov_b32 m0, s63
	v_add_u32_e32 v21, 0x36000, v19
	global_load_lds_dwordx4 v20, s[48:49]
	v_add_u32_e32 v20, 12, v17
	v_xor_b32_e32 v20, v20, v16
	v_lshlrev_b32_e32 v20, 3, v20
	v_and_or_b32 v20, v20, s84, v21
	v_lshlrev_b32_e32 v20, 1, v20
	s_mov_b32 m0, s91
	v_add_u32_e32 v19, 0x6c000, v19
	global_load_lds_dwordx4 v20, s[48:49]
	s_mov_b32 m0, s33
	s_nop 0
	global_load_lds_dwordx4 v18, s[48:49]
	v_add_u32_e32 v18, 20, v17
	v_xor_b32_e32 v18, v18, v16
	v_lshlrev_b32_e32 v18, 3, v18
	v_and_or_b32 v18, v18, s84, v21
	v_lshl_add_u32 v18, v18, 1, v243
	s_mov_b32 m0, s97
	s_nop 0
	global_load_lds_dwordx4 v18, s[48:49]
	v_add_u32_e32 v18, 24, v17
	v_xor_b32_e32 v18, v18, v16
	v_add_u32_e32 v17, 28, v17
	v_lshlrev_b32_e32 v18, 3, v18
	v_xor_b32_e32 v16, v17, v16
	v_and_or_b32 v18, v18, s84, v19
	v_lshlrev_b32_e32 v16, 3, v16
	v_lshlrev_b32_e32 v18, 1, v18
	s_mov_b32 m0, s89
	v_and_or_b32 v16, v16, s84, v19
	global_load_lds_dwordx4 v18, s[48:49]
	v_lshl_add_u32 v16, v16, 1, v254
	s_mov_b32 m0, s73
	s_nop 0
	global_load_lds_dwordx4 v16, s[48:49]
